# prefix phase: 32 partial-state loads and their address arithmetic hoisted above the decay log-sigmoid math (wait becomes vmcnt(32), math temps renamed to free v130/v132-143)
# baseline (speedup 1.0000x reference)
; __device__ __forceinline__ float log_sigmoid(float x) { return fminf(x, 0.f) - log1pf(expf(-fabsf(x))); }
; __device__ __forceinline__ void ret_prefix_phase(float* RETC, const float* decay_l, int gt, int ngt) {
;     for (int i = gt; i < 32 * 2 * 4096; i += ngt) { const int e = i & 4095, dir = (i >> 12) & 1, bh = i >> 13, h = bh & 3;
;         const float G = __expf(log_sigmoid(decay_l[dir * 4 + h]) * 128.f); float* base = RETC + (size_t)bh * 34 * 8192 + dir * 4096 + e;
;         float cv[34];
; #pragma unroll
;         for (int x = 0; x < 34; ++x) cv[x] = base[(size_t)x * 8192];
;         float s = 0.f;
.LBB0_631:
	v_ashrrev_i32_e32 v17, 13, v70
	v_mul_i32_i24_e32 v4, 34, v17
	v_ashrrev_i32_e32 v5, 31, v4
	v_bfe_u32 v16, v70, 12, 1
	v_lshlrev_b64 v[4:5], 15, v[4:5]
	v_and_b32_e32 v6, 0xfff, v70
	v_lshl_add_u64 v[4:5], s[40:41], 0, v[4:5]
	v_lshlrev_b32_e32 v0, 14, v16
	v_lshl_add_u64 v[4:5], v[4:5], 0, v[0:1]
	v_lshlrev_b32_e32 v0, 2, v6
	v_lshl_add_u64 v[4:5], v[4:5], 0, v[0:1]
	v_lshlrev_b32_e32 v0, 2, v17
	v_and_b32_e32 v0, 12, v0
	v_lshl_or_b32 v0, v16, 4, v0
	global_load_dword v97, v0, s[82:83]
	s_mov_b32 s8, 0x8000
	v_add_co_u32_e32 v6, vcc, s8, v4
	s_mov_b32 s8, 0x10000
	s_nop 0
	v_addc_co_u32_e32 v7, vcc, 0, v5, vcc
	v_add_co_u32_e32 v8, vcc, s8, v4
	s_mov_b32 s8, 0x18000
	s_nop 0
	v_addc_co_u32_e32 v9, vcc, 0, v5, vcc
	v_add_co_u32_e32 v10, vcc, s8, v4
	s_mov_b32 s8, 0x20000
	s_nop 0
	v_addc_co_u32_e32 v11, vcc, 0, v5, vcc
	v_add_co_u32_e32 v12, vcc, s8, v4
	s_mov_b32 s8, 0x28000
	s_nop 0
	v_addc_co_u32_e32 v13, vcc, 0, v5, vcc
	v_add_co_u32_e32 v14, vcc, s8, v4
	s_mov_b32 s8, 0x30000
	s_nop 0
	v_addc_co_u32_e32 v15, vcc, 0, v5, vcc
	s_mov_b64 s[2:3], 0x28000
	v_and_b32_e32 v105, 0x1000, v70
	v_add_co_u32_e32 v16, vcc, s8, v4
	s_mov_b32 s8, 0x38000
	s_nop 0
	v_addc_co_u32_e32 v17, vcc, 0, v5, vcc
	v_add_co_u32_e32 v18, vcc, s8, v4
	s_mov_b32 s8, 0x60000
	s_nop 0
	v_addc_co_u32_e32 v19, vcc, 0, v5, vcc
	v_add_co_u32_e32 v20, vcc, s54, v4
	s_nop 1
	v_addc_co_u32_e32 v21, vcc, 0, v5, vcc
	v_add_co_u32_e32 v22, vcc, s55, v4
	s_nop 1
	v_addc_co_u32_e32 v23, vcc, 0, v5, vcc
	v_add_co_u32_e32 v24, vcc, s59, v4
	s_nop 1
	v_addc_co_u32_e32 v25, vcc, 0, v5, vcc
	v_add_co_u32_e32 v26, vcc, s61, v4
	s_nop 1
	v_addc_co_u32_e32 v27, vcc, 0, v5, vcc
	v_add_co_u32_e32 v28, vcc, s8, v4
	s_mov_b32 s8, 0x68000
	s_nop 0
	v_addc_co_u32_e32 v29, vcc, 0, v5, vcc
	v_add_co_u32_e32 v30, vcc, s8, v4
	s_mov_b32 s8, 0x70000
	s_nop 0
	v_addc_co_u32_e32 v31, vcc, 0, v5, vcc
	v_add_co_u32_e32 v32, vcc, s8, v4
	s_mov_b32 s8, 0x78000
	s_nop 0
	v_addc_co_u32_e32 v33, vcc, 0, v5, vcc
	v_add_co_u32_e32 v34, vcc, s8, v4
	s_mov_b32 s8, 0x80000
	s_nop 0
	v_addc_co_u32_e32 v35, vcc, 0, v5, vcc
	v_add_co_u32_e32 v36, vcc, s8, v4
	s_mov_b32 s8, 0x88000
	s_nop 0
	v_addc_co_u32_e32 v37, vcc, 0, v5, vcc
	v_add_co_u32_e32 v38, vcc, s8, v4
	s_mov_b32 s8, 0x90000
	s_nop 0
	v_addc_co_u32_e32 v39, vcc, 0, v5, vcc
	v_add_co_u32_e32 v40, vcc, s8, v4
	s_mov_b32 s8, 0x98000
	s_nop 0
	v_addc_co_u32_e32 v41, vcc, 0, v5, vcc
	v_add_co_u32_e32 v42, vcc, s8, v4
	s_mov_b32 s8, 0xa0000
	s_nop 0
	v_addc_co_u32_e32 v43, vcc, 0, v5, vcc
	v_add_co_u32_e32 v44, vcc, s8, v4
	s_mov_b32 s8, 0xa8000
	s_nop 0
	v_addc_co_u32_e32 v45, vcc, 0, v5, vcc
	v_add_co_u32_e32 v46, vcc, s8, v4
	s_mov_b32 s8, 0xb0000
	s_nop 0
	v_addc_co_u32_e32 v47, vcc, 0, v5, vcc
	v_add_co_u32_e32 v48, vcc, s8, v4
	s_mov_b32 s8, 0xb8000
	s_nop 0
	v_addc_co_u32_e32 v49, vcc, 0, v5, vcc
	v_add_co_u32_e32 v50, vcc, s8, v4
	s_mov_b32 s8, 0xc0000
	s_nop 0
	v_addc_co_u32_e32 v51, vcc, 0, v5, vcc
	v_add_co_u32_e32 v52, vcc, s8, v4
	s_mov_b32 s8, 0xc8000
	s_nop 0
	v_addc_co_u32_e32 v53, vcc, 0, v5, vcc
	v_add_co_u32_e32 v54, vcc, s8, v4
	s_mov_b32 s8, 0xd0000
	s_nop 0
	v_addc_co_u32_e32 v55, vcc, 0, v5, vcc
	v_add_co_u32_e32 v56, vcc, s8, v4
	s_mov_b32 s8, 0xd8000
	s_nop 0
	v_addc_co_u32_e32 v57, vcc, 0, v5, vcc
	v_add_co_u32_e32 v58, vcc, s8, v4
	s_mov_b32 s8, 0xe0000
	s_nop 0
	v_addc_co_u32_e32 v59, vcc, 0, v5, vcc
	v_add_co_u32_e32 v60, vcc, s8, v4
	s_mov_b32 s8, 0xe8000
	s_nop 0
	v_addc_co_u32_e32 v61, vcc, 0, v5, vcc
	v_add_co_u32_e32 v62, vcc, s8, v4
	s_mov_b32 s8, 0xf0000
	s_nop 0
	v_addc_co_u32_e32 v63, vcc, 0, v5, vcc
	v_add_co_u32_e32 v64, vcc, s8, v4
	s_mov_b64 s[8:9], 0x18000
	s_nop 0
	v_addc_co_u32_e32 v65, vcc, 0, v5, vcc
	v_add_co_u32_e32 v66, vcc, 0x100000, v4
	s_nop 1
	v_addc_co_u32_e32 v67, vcc, 0, v5, vcc
	v_add_co_u32_e32 v68, vcc, 0x108000, v4
	s_nop 1
	v_addc_co_u32_e32 v69, vcc, 0, v5, vcc
	global_load_dword v0, v[6:7], off
	global_load_dword v71, v[8:9], off
	global_load_dword v72, v[10:11], off
	global_load_dword v73, v[12:13], off
	global_load_dword v74, v[14:15], off
	global_load_dword v75, v[16:17], off
	global_load_dword v76, v[18:19], off
	global_load_dword v77, v[20:21], off
	global_load_dword v78, v[22:23], off
	global_load_dword v80, v[24:25], off
	global_load_dword v81, v[26:27], off
	global_load_dword v82, v[28:29], off
	global_load_dword v83, v[30:31], off
	global_load_dword v84, v[32:33], off
	global_load_dword v85, v[34:35], off
	global_load_dword v86, v[36:37], off
	global_load_dword v87, v[38:39], off
	global_load_dword v88, v[40:41], off
	global_load_dword v89, v[42:43], off
	global_load_dword v90, v[44:45], off
	global_load_dword v91, v[46:47], off
	global_load_dword v92, v[48:49], off
	global_load_dword v93, v[50:51], off
	global_load_dword v94, v[52:53], off
	global_load_dword v95, v[54:55], off
	global_load_dword v96, v[56:57], off
	global_load_dword v98, v[58:59], off
	global_load_dword v99, v[60:61], off
	global_load_dword v100, v[62:63], off
	global_load_dword v101, v[64:65], off
	global_load_dword v79, v[66:67], off
	global_load_dword v103, v[68:69], off
	s_waitcnt vmcnt(32)
; __device__ __forceinline__ float log_sigmoid(float x) { return fminf(x, 0.f) - log1pf(expf(-fabsf(x))); }
; __device__ __forceinline__ void ret_prefix_phase(float* RETC, const float* decay_l, int gt, int ngt) {
;     ...
;         const float G = __expf(log_sigmoid(decay_l[dir * 4 + h]) * 128.f); float* base = RETC + (size_t)bh * 34 * 8192 + dir * 4096 + e;
;         float cv[34];
; #pragma unroll
;         for (int x = 0; x < 34; ++x) cv[x] = base[(size_t)x * 8192];
;         float s = 0.f;
	v_mul_f32_e64 v130, |v97|, s35
	v_fma_f32 v132, |v97|, s35, -v130
	v_rndne_f32_e32 v133, v130
	v_fma_f32 v132, |v97|, s37, v132
	v_sub_f32_e32 v130, v130, v133
	v_add_f32_e32 v130, v130, v132
	v_cvt_i32_f32_e32 v133, v133
	v_exp_f32_e32 v130, v130
	v_cmp_ngt_f32_e64 vcc, |v97|, s38
	v_ldexp_f32 v130, v130, v133
	s_nop 0
	v_cndmask_b32_e32 v130, 0, v130, vcc
	v_cmp_nlt_f32_e64 vcc, |v97|, s39
	s_nop 1
	v_cndmask_b32_e32 v130, v219, v130, vcc
	v_add_f32_e32 v134, 1.0, v130
	v_cvt_f64_f32_e32 v[132:133], v134
	v_frexp_mant_f32_e32 v135, v134
	v_frexp_exp_i32_f64_e32 v132, v[132:133]
	v_add_f32_e32 v133, -1.0, v134
	v_cmp_gt_f32_e32 vcc, s48, v135
	v_sub_f32_e32 v135, v133, v134
	v_sub_f32_e32 v133, v130, v133
	v_subbrev_co_u32_e32 v132, vcc, 0, v132, vcc
	v_add_f32_e32 v135, 1.0, v135
	v_add_f32_e32 v133, v133, v135
	v_sub_u32_e32 v135, 0, v132
	v_cvt_f32_i32_e32 v132, v132
	v_ldexp_f32 v134, v134, v135
	v_ldexp_f32 v133, v133, v135
	v_add_f32_e32 v135, -1.0, v134
	v_add_f32_e32 v136, 1.0, v134
	v_add_f32_e32 v137, 1.0, v135
	v_add_f32_e32 v138, -1.0, v136
	v_sub_f32_e32 v137, v134, v137
	v_sub_f32_e32 v134, v134, v138
	v_mul_f32_e32 v138, 0x3f317218, v132
	v_add_f32_e32 v137, v133, v137
	v_add_f32_e32 v133, v133, v134
	v_fma_f32 v134, v132, s49, -v138
	v_add_f32_e32 v139, v135, v137
	v_add_f32_e32 v140, v136, v133
	v_fmac_f32_e32 v134, 0xb102e308, v132
	v_sub_f32_e32 v132, v135, v139
	v_sub_f32_e32 v135, v136, v140
	v_rcp_f32_e32 v136, v140
	v_add_f32_e32 v141, v138, v134
	v_add_f32_e32 v133, v133, v135
	v_sub_f32_e32 v135, v141, v138
	v_sub_f32_e32 v134, v134, v135
	v_mul_f32_e32 v135, v139, v136
	v_add_f32_e32 v132, v137, v132
	v_mul_f32_e32 v137, v140, v135
	v_fma_f32 v138, v135, v140, -v137
	v_fmac_f32_e32 v138, v135, v133
	v_add_f32_e32 v142, v137, v138
	v_sub_f32_e32 v143, v139, v142
	v_sub_f32_e32 v137, v142, v137
	v_sub_f32_e32 v139, v139, v143
	v_sub_f32_e32 v137, v137, v138
	v_sub_f32_e32 v138, v139, v142
	v_add_f32_e32 v132, v132, v138
	v_add_f32_e32 v132, v137, v132
	v_add_f32_e32 v137, v143, v132
	v_mul_f32_e32 v138, v136, v137
	v_sub_f32_e32 v139, v143, v137
	v_mul_f32_e32 v142, v140, v138
	v_add_f32_e32 v132, v132, v139
	v_add_f32_e32 v139, v135, v138
	v_fma_f32 v140, v138, v140, -v142
	v_sub_f32_e32 v135, v139, v135
	v_fmac_f32_e32 v140, v138, v133
	v_sub_f32_e32 v133, v138, v135
	v_add_f32_e32 v135, v142, v140
	v_sub_f32_e32 v138, v135, v142
	v_sub_f32_e32 v142, v137, v135
	v_sub_f32_e32 v137, v137, v142
	v_sub_f32_e32 v135, v137, v135
	v_sub_f32_e32 v138, v138, v140
	v_add_f32_e32 v132, v132, v135
	v_add_f32_e32 v132, v138, v132
	v_add_f32_e32 v132, v142, v132
	v_mul_f32_e32 v132, v136, v132
	v_add_f32_e32 v132, v133, v132
	v_add_f32_e32 v133, v139, v132
	v_mul_f32_e32 v135, v133, v133
	v_fmamk_f32 v138, v135, 0x3e9b6dac, v217
	v_sub_f32_e32 v136, v133, v139
	v_ldexp_f32 v137, v133, 1
	v_mul_f32_e32 v133, v133, v135
	v_fmaak_f32 v135, v135, v138, 0x3f2aaada
	v_mul_f32_e32 v133, v133, v135
	v_add_f32_e32 v135, v137, v133
	v_sub_f32_e32 v132, v132, v136
	v_sub_f32_e32 v136, v135, v137
	v_ldexp_f32 v132, v132, 1
	v_sub_f32_e32 v133, v133, v136
	v_add_f32_e32 v132, v132, v133
	v_add_f32_e32 v133, v135, v132
	v_sub_f32_e32 v135, v133, v135
	v_add_f32_e32 v136, v141, v133
	v_sub_f32_e32 v132, v132, v135
	v_sub_f32_e32 v135, v136, v141
	v_sub_f32_e32 v137, v136, v135
	v_sub_f32_e32 v133, v133, v135
	v_add_f32_e32 v135, v134, v132
	v_sub_f32_e32 v137, v141, v137
	v_sub_f32_e32 v138, v135, v134
	v_add_f32_e32 v133, v133, v137
	v_sub_f32_e32 v137, v135, v138
	v_sub_f32_e32 v132, v132, v138
	v_sub_f32_e32 v134, v134, v137
	v_add_f32_e32 v133, v135, v133
	v_add_f32_e32 v132, v132, v134
	v_add_f32_e32 v134, v136, v133
	v_sub_f32_e32 v135, v134, v136
	v_sub_f32_e32 v133, v133, v135
	v_add_f32_e32 v132, v132, v133
	v_add_f32_e32 v132, v134, v132
	v_cmp_neq_f32_e32 vcc, s46, v130
	s_nop 1
	v_cndmask_b32_e32 v132, v219, v132, vcc
	v_cmp_lt_f32_e64 vcc, |v130|, s50
	s_nop 1
	v_cndmask_b32_e32 v102, v132, v130, vcc
	v_lshl_add_u64 v[12:13], v[4:5], 0, s[8:9]
	s_mov_b64 s[8:9], 0x30000
	v_lshl_add_u64 v[18:19], v[4:5], 0, s[8:9]
	s_mov_b64 s[8:9], 0x38000
	v_lshl_add_u64 v[20:21], v[4:5], 0, s[8:9]
	s_mov_b64 s[8:9], 0x60000
	v_lshl_add_u64 v[30:31], v[4:5], 0, s[8:9]
	s_mov_b64 s[8:9], 0x68000
	v_lshl_add_u64 v[32:33], v[4:5], 0, s[8:9]
	s_mov_b64 s[8:9], 0x70000
	v_lshl_add_u64 v[34:35], v[4:5], 0, s[8:9]
	s_mov_b64 s[8:9], 0x78000
	v_lshl_add_u64 v[36:37], v[4:5], 0, s[8:9]
	s_mov_b64 s[8:9], 0x80000
	v_lshl_add_u64 v[38:39], v[4:5], 0, s[8:9]
	s_mov_b64 s[8:9], 0x88000
	v_lshl_add_u64 v[40:41], v[4:5], 0, s[8:9]
	s_mov_b64 s[8:9], 0x90000
	v_lshl_add_u64 v[42:43], v[4:5], 0, s[8:9]
	s_mov_b64 s[8:9], 0x98000
	v_lshl_add_u64 v[44:45], v[4:5], 0, s[8:9]
	s_mov_b64 s[8:9], 0xa0000
	v_lshl_add_u64 v[46:47], v[4:5], 0, s[8:9]
	s_mov_b64 s[8:9], 0xa8000
	v_max_f32_e32 v6, v97, v97
	v_lshl_add_u64 v[48:49], v[4:5], 0, s[8:9]
	s_mov_b64 s[8:9], 0xb0000
	v_min_f32_e32 v6, 0, v6
	v_lshl_add_u64 v[50:51], v[4:5], 0, s[8:9]
	s_mov_b64 s[8:9], 0xb8000
	v_sub_f32_e32 v6, v6, v102
	v_lshl_add_u64 v[52:53], v[4:5], 0, s[8:9]
	s_mov_b64 s[8:9], 0xc0000
	v_mul_f32_e32 v6, 0x43000000, v6
	v_lshl_add_u64 v[54:55], v[4:5], 0, s[8:9]
	s_mov_b64 s[8:9], 0xc8000
	v_mul_f32_e32 v66, 0x3fb8aa3b, v6
	v_lshl_add_u64 v[56:57], v[4:5], 0, s[8:9]
	s_mov_b64 s[8:9], 0xd0000
	v_lshl_add_u64 v[58:59], v[4:5], 0, s[8:9]
	s_mov_b64 s[8:9], 0xd8000
	v_exp_f32_e32 v97, v66
	v_lshl_add_u64 v[16:17], v[4:5], 0, s[2:3]
	s_mov_b64 s[2:3], 0x48000
	v_lshl_add_u64 v[60:61], v[4:5], 0, s[8:9]
	s_mov_b64 s[8:9], 0xe0000
	v_lshl_add_u64 v[24:25], v[4:5], 0, s[2:3]
	s_mov_b64 s[2:3], 0x50000
	v_lshl_add_u64 v[62:63], v[4:5], 0, s[8:9]
	s_mov_b64 s[8:9], 0xe8000
	v_lshl_add_u64 v[26:27], v[4:5], 0, s[2:3]
	s_mov_b64 s[2:3], 0x58000
	v_lshl_add_u64 v[64:65], v[4:5], 0, s[8:9]
	s_mov_b64 s[8:9], 0xf8000
	v_lshl_add_u64 v[8:9], v[4:5], 0, s[66:67]
	v_lshl_add_u64 v[10:11], v[4:5], 0, s[70:71]
	v_lshl_add_u64 v[14:15], v[4:5], 0, s[96:97]
	v_lshl_add_u64 v[22:23], v[4:5], 0, s[68:69]
	v_lshl_add_u64 v[28:29], v[4:5], 0, s[2:3]
	v_lshl_add_u64 v[6:7], v[4:5], 0, s[8:9]
	v_lshl_add_u64 v[66:67], v[4:5], 0, s[74:75]
	v_lshl_add_u64 v[68:69], v[4:5], 0, s[62:63]
	v_mul_f32_e32 v104, 0, v97
	v_cmp_ne_u32_e32 vcc, 0, v105
	s_and_saveexec_b64 s[8:9], vcc
	s_xor_b64 s[8:9], exec, s[8:9]
	s_cbranch_execz .LBB0_633
; __device__ __forceinline__ void ret_prefix_phase(float* RETC, const float* decay_l, int gt, int ngt) {
;     ...
;         else {
; #pragma unroll
;             for (int k = 0; k < 34; ++k) { const int x = 33 - k; base[(size_t)x * 8192] = s; s = s * G + cv[x]; } }
	global_load_dword v102, v[6:7], off
	s_nop 0
	global_store_dword v[68:69], v1, off
	s_waitcnt vmcnt(2)
	v_add_f32_e32 v68, v103, v104
	v_fmac_f32_e32 v79, v97, v68
	global_store_dword v[66:67], v68, off
	s_waitcnt vmcnt(2)
	v_fmac_f32_e32 v102, v97, v79
	v_fmac_f32_e32 v101, v97, v102
	v_fmac_f32_e32 v100, v97, v101
	v_fmac_f32_e32 v99, v97, v100
	v_fmac_f32_e32 v98, v97, v99
	v_fmac_f32_e32 v96, v97, v98
	v_fmac_f32_e32 v95, v97, v96
	v_fmac_f32_e32 v94, v97, v95
	v_fmac_f32_e32 v93, v97, v94
	v_fmac_f32_e32 v92, v97, v93
	v_fmac_f32_e32 v91, v97, v92
	v_fmac_f32_e32 v90, v97, v91
	v_fmac_f32_e32 v89, v97, v90
	v_fmac_f32_e32 v88, v97, v89
	v_fmac_f32_e32 v87, v97, v88
	v_fmac_f32_e32 v86, v97, v87
	v_fmac_f32_e32 v85, v97, v86
	v_fmac_f32_e32 v84, v97, v85
	v_fmac_f32_e32 v83, v97, v84
	v_fmac_f32_e32 v82, v97, v83
	v_fmac_f32_e32 v81, v97, v82
	v_fmac_f32_e32 v80, v97, v81
	v_fmac_f32_e32 v78, v97, v80
	v_fmac_f32_e32 v77, v97, v78
	v_fmac_f32_e32 v76, v97, v77
	v_fmac_f32_e32 v75, v97, v76
	v_fmac_f32_e32 v74, v97, v75
	v_fmac_f32_e32 v73, v97, v74
	v_fmac_f32_e32 v72, v97, v73
	v_fmac_f32_e32 v71, v97, v72
	v_fmac_f32_e32 v0, v97, v71
	global_store_dword v[64:65], v101, off
	global_store_dword v[62:63], v100, off
	global_store_dword v[60:61], v99, off
	global_store_dword v[58:59], v98, off
	global_store_dword v[56:57], v96, off
	global_store_dword v[54:55], v95, off
	global_store_dword v[52:53], v94, off
	global_store_dword v[50:51], v93, off
	global_store_dword v[48:49], v92, off
	global_store_dword v[46:47], v91, off
	global_store_dword v[44:45], v90, off
	global_store_dword v[42:43], v89, off
	global_store_dword v[40:41], v88, off
	global_store_dword v[38:39], v87, off
	global_store_dword v[36:37], v86, off
	global_store_dword v[34:35], v85, off
	global_store_dword v[32:33], v84, off
	global_store_dword v[30:31], v83, off
	global_store_dword v[28:29], v82, off
	global_store_dword v[26:27], v81, off
	global_store_dword v[24:25], v80, off
	global_store_dword v[22:23], v78, off
	global_store_dword v[20:21], v77, off
	global_store_dword v[18:19], v76, off
	global_store_dword v[16:17], v75, off
	global_store_dword v[14:15], v74, off
	global_store_dword v[12:13], v73, off
	global_store_dword v[10:11], v72, off
	global_store_dword v[8:9], v71, off
	global_store_dword v[4:5], v0, off
